# attention: V staging LDS writes issued after the round's Q/K0/K1 loads instead of before them
# baseline (speedup 1.0000x reference)
; #define LAS __attribute__((address_space(3)))
; #define ATT_LOADK(buf, grp) do { _Pragma("unroll") for (int tt = 0; tt < 3; ++tt) { int ki = kbase + 16 * ((grp) * 3 + tt); ki = ki < 0 ? 0 : (ki > a.m - 1 ? a.m - 1 : ki); \
;             const bf16_t* kp = kcol + (size_t)ki * 128; \
;             _Pragma("unroll") for (int ks = 0; ks < 4; ++ks) Kf[buf][tt][ks] = *(const bf16x8*)(kp + 32 * ks); } } while (0)
; __device__ __forceinline__ void attn_phase(LAS unsigned char* lds, bf16_t* qkv, float* lse, const float* biasT, int G) {
;     ...
;         const int pair = attn_pair(j, cwg, G); if (pair >= 4608) break;
;         const int pairn = (j + 1 < nrounds) ? attn_pair(j + 1, cwg, G) : 4608;
;         const AttnItem a = attn_item(pair * 2 + half);
; #pragma unroll
;         for (int pass = 0; pass < 12; ++pass) *(LAS u32x4*)(vs + (pass * 16 + (ht >> 4)) * VS_PITCH + (ht & 15) * 16) = vreg[pass];
;         if (ht < 129) bs[16 + ht] = biasT[a.head * 132 + ht];
;         __syncthreads();
;         const size_t tokq = (size_t)(a.pos0 + a.r + ((16 * w4 + li) << a.dsh));
;         const int pbase = a.seq_base + a.r * a.m;
;         bf16_t* qp = qkv + ((size_t)a.head * M_TOK + pbase + a.i0 + 16 * w4 + li) * 128;
;         bf16x8 Qf[4];
; #pragma unroll
;         for (int ks = 0; ks < 4; ++ks) Qf[ks] = *(const bf16x8*)(qp + 32 * ks + 8 * lg);
;         const int kbase = a.i0 - 64 + 16 * w4 + li;
;         const bf16_t* kcol = qkv + ((size_t)(12 + a.head) * M_TOK + pbase) * 128 + 8 * lg;
;         f32x4 sa[10];
;         bf16x8 Kf[2][3][4];
;     ...
;         ATT_LOADK(0, 0); ATT_LOADK(1, 1);
.LBB0_423:
	s_lshl_b32 s9, s11, 1
	s_add_i32 s9, s9, s94
	s_mul_hi_i32 s0, s9, 0x2aaaaaab
	s_lshr_b32 s1, s0, 31
	s_ashr_i32 s0, s0, 7
	s_add_i32 s10, s0, s1
	s_waitcnt vmcnt(9)
	s_mov_b64 s[0:1], exec
	v_readlane_b32 s12, v250, 1
	v_readlane_b32 s13, v250, 2
	s_and_b64 s[12:13], s[0:1], s[12:13]
	s_mov_b64 exec, s[12:13]
	s_cbranch_execz .LBB0_425
	s_mul_i32 s11, s10, 0x84
	v_add_u32_e32 v2, s11, v183
	v_readlane_b32 s12, v250, 13
	v_ashrrev_i32_e32 v3, 31, v2
	v_readlane_b32 s13, v250, 14
	s_nop 1
	v_lshl_add_u64 v[2:3], v[2:3], 2, s[12:13]
	global_load_dword v253, v[2:3], off
.LBB0_425:
	s_or_b64 exec, exec, s[0:1]
	s_mul_i32 s0, s10, 0xfffffd00
	s_add_i32 s0, s0, s9
	s_lshl_b32 s1, s0, 6
	s_and_b32 s9, s1, 0xffffe000
	s_cmpk_lt_i32 s0, 0x200
	s_cselect_b32 s0, 13, 14
	s_cselect_b32 s9, s9, 0x8000
	s_ashr_i32 s11, s10, 1
	s_and_b32 s12, s11, -2
	s_sub_i32 s11, s0, s12
	s_sub_i32 s30, s1, s9
	s_ashr_i32 s96, s30, s11
	s_lshl_b32 s31, s96, s11
	s_sub_i32 s13, s30, s31
	s_add_i32 s16, s31, s9
	s_mul_hi_i32 s0, s10, 0xc000
	s_ashr_i32 s18, s16, 31
	s_ashr_i32 s1, s13, 31
	s_mul_i32 s17, s10, 0xc000
	v_mov_b32_e32 v3, s0
	s_add_u32 s0, s13, s16
	v_or_b32_e32 v2, s17, v184
	s_addc_u32 s1, s1, s18
	v_lshl_add_u64 v[2:3], s[0:1], 0, v[2:3]
	v_readlane_b32 s0, v250, 21
	s_add_i32 s15, s13, s0
	s_add_i32 s0, s10, 12
	s_add_i32 s17, s17, 0x90000
	v_lshlrev_b64 v[2:3], 8, v[2:3]
	s_mul_hi_i32 s1, s0, 0xc000
	s_add_u32 s0, s17, s16
	v_lshl_add_u64 v[194:195], s[92:93], 0, v[2:3]
	v_mov_b32_e32 v191, v1
	s_addc_u32 s1, s1, s18
	v_lshl_add_u64 v[2:3], v[194:195], 0, v[190:191]
	s_lshl_b64 s[0:1], s[0:1], 8
	global_load_dwordx4 v[96:99], v[2:3], off
	global_load_dwordx4 v[92:95], v[2:3], off offset:64
	global_load_dwordx4 v[88:91], v[2:3], off offset:128
	global_load_dwordx4 v[52:55], v[2:3], off offset:192
	v_add_u32_e32 v0, s15, v216
	v_lshl_add_u64 v[2:3], v[186:187], 0, s[0:1]
	s_bfm_b32 s0, s11, 0
	v_min_i32_e32 v56, s0, v0
	v_ashrrev_i32_e32 v57, 31, v56
	v_lshlrev_b64 v[56:57], 7, v[56:57]
	v_cmp_lt_i32_e32 vcc, -1, v0
	s_movk_i32 s1, 0xffef
	v_add_u32_e32 v58, 48, v0
	v_cndmask_b32_e32 v57, 0, v57, vcc
	v_cndmask_b32_e32 v56, 0, v56, vcc
	v_lshl_add_u64 v[56:57], v[56:57], 1, v[2:3]
	global_load_dwordx4 v[68:71], v[56:57], off
	global_load_dwordx4 v[72:75], v[56:57], off offset:64
	global_load_dwordx4 v[80:83], v[56:57], off offset:128
	global_load_dwordx4 v[84:87], v[56:57], off offset:192
	v_add_u32_e32 v56, 16, v0
	v_min_i32_e32 v56, s0, v56
	v_ashrrev_i32_e32 v57, 31, v56
	v_lshlrev_b64 v[56:57], 7, v[56:57]
	v_cmp_lt_i32_e32 vcc, s1, v0
	s_movk_i32 s1, 0xffdf
	v_add_u32_e32 v102, 64, v0
	v_cndmask_b32_e32 v57, 0, v57, vcc
	v_cndmask_b32_e32 v56, 0, v56, vcc
	v_lshl_add_u64 v[56:57], v[56:57], 1, v[2:3]
	global_load_dwordx4 v[116:119], v[56:57], off
	global_load_dwordx4 v[136:139], v[56:57], off offset:64
	global_load_dwordx4 v[140:143], v[56:57], off offset:128
	global_load_dwordx4 v[144:147], v[56:57], off offset:192
	v_add_u32_e32 v56, 32, v0
	v_min_i32_e32 v56, s0, v56
	v_ashrrev_i32_e32 v57, 31, v56
	v_lshlrev_b64 v[56:57], 7, v[56:57]
	v_cmp_lt_i32_e32 vcc, s1, v0
	v_min_i32_e32 v100, s0, v102
	v_add_u32_e32 v122, 0x50, v0
	v_cndmask_b32_e32 v57, 0, v57, vcc
	v_cndmask_b32_e32 v56, 0, v56, vcc
	v_lshl_add_u64 v[56:57], v[56:57], 1, v[2:3]
	global_load_dwordx4 v[148:151], v[56:57], off
	global_load_dwordx4 v[152:155], v[56:57], off offset:64
	global_load_dwordx4 v[156:159], v[56:57], off offset:128
	global_load_dwordx4 v[160:163], v[56:57], off offset:192
	v_min_i32_e32 v56, s0, v58
	v_ashrrev_i32_e32 v57, 31, v56
	v_lshlrev_b64 v[56:57], 7, v[56:57]
	v_cmp_lt_i32_e32 vcc, -1, v58
	v_ashrrev_i32_e32 v101, 31, v100
	v_min_i32_e32 v120, s0, v122
	v_cndmask_b32_e32 v57, 0, v57, vcc
	v_cndmask_b32_e32 v56, 0, v56, vcc
	v_lshlrev_b64 v[100:101], 7, v[100:101]
	v_cmp_lt_i32_e32 vcc, -1, v102
	v_ashrrev_i32_e32 v121, 31, v120
	v_lshlrev_b64 v[120:121], 7, v[120:121]
	v_cndmask_b32_e32 v101, 0, v101, vcc
	v_cndmask_b32_e32 v100, 0, v100, vcc
	v_cmp_lt_i32_e32 vcc, -1, v122
	v_lshl_add_u64 v[76:77], v[56:57], 1, v[2:3]
	v_lshl_add_u64 v[112:113], v[100:101], 1, v[2:3]
	v_cndmask_b32_e32 v121, 0, v121, vcc
	v_cndmask_b32_e32 v120, 0, v120, vcc
	v_lshl_add_u64 v[132:133], v[120:121], 1, v[2:3]
	global_load_dwordx4 v[56:59], v[76:77], off
	global_load_dwordx4 v[60:63], v[76:77], off offset:64
	global_load_dwordx4 v[64:67], v[76:77], off offset:128
	s_nop 0
	global_load_dwordx4 v[76:79], v[76:77], off offset:192
	s_nop 0
	global_load_dwordx4 v[100:103], v[112:113], off
	global_load_dwordx4 v[104:107], v[112:113], off offset:64
	global_load_dwordx4 v[108:111], v[112:113], off offset:128
	s_nop 0
	global_load_dwordx4 v[112:115], v[112:113], off offset:192
	s_nop 0
	global_load_dwordx4 v[120:123], v[132:133], off
	global_load_dwordx4 v[124:127], v[132:133], off offset:64
	global_load_dwordx4 v[128:131], v[132:133], off offset:128
	s_nop 0
	global_load_dwordx4 v[132:135], v[132:133], off offset:192
	ds_write_b128 v231, v[8:11]
	ds_write_b128 v231, v[4:7] offset:4608
	ds_write_b128 v231, v[12:15] offset:9216
	ds_write_b128 v231, v[16:19] offset:13824
	ds_write_b128 v231, v[20:23] offset:18432
	ds_write_b128 v231, v[24:27] offset:23040
	ds_write_b128 v231, v[28:31] offset:27648
	ds_write_b128 v231, v[32:35] offset:32256
	ds_write_b128 v231, v[36:39] offset:36864
	ds_write_b128 v231, v[40:43] offset:41472
	ds_write_b128 v231, v[44:47] offset:46080
	ds_write_b128 v231, v[48:51] offset:50688
	s_waitcnt vmcnt(23)
; #define ATT_LOADK(buf, grp) do { _Pragma("unroll") for (int tt = 0; tt < 3; ++tt) { int ki = kbase + 16 * ((grp) * 3 + tt); ki = ki < 0 ? 0 : (ki > a.m - 1 ? a.m - 1 : ki); \
;             const bf16_t* kp = kcol + (size_t)ki * 128; \
;             _Pragma("unroll") for (int ks = 0; ks < 4; ++ks) Kf[buf][tt][ks] = *(const bf16x8*)(kp + 32 * ks); } } while (0)
; #define ATT_MMAK(buf, grp) do { _Pragma("unroll") for (int tt = 0; tt < 3; ++tt) { f32x4 acc_ = (f32x4){0.f, 0.f, 0.f, 0.f}; \
;             _Pragma("unroll") for (int ks = 0; ks < 4; ++ks) acc_ = __builtin_amdgcn_mfma_f32_16x16x32_bf16(Kf[buf][tt][ks], Qf[ks], acc_, 0, 0, 0); sa[(grp) * 3 + tt] = acc_; } } while (0)
; __device__ __forceinline__ void attn_load_v(const AttnItem& a, const bf16_t* qkv, int ht, u32x4 (&vreg)[12]) {
; #pragma unroll
;     for (int pass = 0; pass < 12; ++pass) {
;         const int row = pass * 16 + (ht >> 4), ch = ht & 15, ki = a.i0 - 64 + row;
;         u32x4 val = (u32x4){0u, 0u, 0u, 0u};
;         if (ki >= 0 && ki < a.m) val = *(const u32x4*)(qkv + ((size_t)(24 + a.head) * M_TOK + a.seq_base + a.r * a.m + ki) * 128 + ch * 8);
;         vreg[pass] = val;
;     }
; }
; __device__ __forceinline__ void attn_phase(LAS unsigned char* lds, bf16_t* qkv, float* lse, const float* biasT, int G) {
;     ...
;         ATT_MMAK(0, 0);
;         __builtin_amdgcn_sched_barrier(0);
;         ATT_LOADK(0, 2);
;         if (pairn < 4608) { const AttnItem an = attn_item(pairn * 2 + half); attn_load_v(an, qkv, ht, vreg); }
	v_mfma_f32_16x16x32_bf16 v[68:71], v[68:71], v[96:99], 0
	s_waitcnt vmcnt(22)
	v_mfma_f32_16x16x32_bf16 v[68:71], v[72:75], v[92:95], v[68:71]
	s_waitcnt vmcnt(21)
	v_mfma_f32_16x16x32_bf16 v[68:71], v[80:83], v[88:91], v[68:71]
	s_waitcnt vmcnt(20)
	v_mfma_f32_16x16x32_bf16 v[84:87], v[84:87], v[52:55], v[68:71]
	s_waitcnt vmcnt(19)
	v_mfma_f32_16x16x32_bf16 v[68:71], v[116:119], v[96:99], 0
	s_waitcnt vmcnt(18)
	v_mfma_f32_16x16x32_bf16 v[68:71], v[136:139], v[92:95], v[68:71]
	s_waitcnt vmcnt(17)
	v_mfma_f32_16x16x32_bf16 v[68:71], v[140:143], v[88:91], v[68:71]
	s_waitcnt vmcnt(16)
	v_mfma_f32_16x16x32_bf16 v[72:75], v[144:147], v[52:55], v[68:71]
	s_waitcnt vmcnt(15)
	v_mfma_f32_16x16x32_bf16 v[68:71], v[148:151], v[96:99], 0
	s_waitcnt vmcnt(14)
	v_mfma_f32_16x16x32_bf16 v[68:71], v[152:155], v[92:95], v[68:71]
	s_waitcnt vmcnt(13)
	v_mfma_f32_16x16x32_bf16 v[68:71], v[156:159], v[88:91], v[68:71]
	s_waitcnt vmcnt(12)
	v_mfma_f32_16x16x32_bf16 v[68:71], v[160:163], v[52:55], v[68:71]
	v_add_u32_e32 v82, 0x60, v0
	v_min_i32_e32 v80, s0, v82
	v_ashrrev_i32_e32 v81, 31, v80
	v_lshlrev_b64 v[80:81], 7, v[80:81]
	v_cmp_lt_i32_e32 vcc, -1, v82
	v_add_u32_e32 v82, 0x70, v0
	v_add_u32_e32 v0, 0x80, v0
	v_cndmask_b32_e32 v81, 0, v81, vcc
	v_cndmask_b32_e32 v80, 0, v80, vcc
	v_lshl_add_u64 v[80:81], v[80:81], 1, v[2:3]
	global_load_dwordx4 v[136:139], v[80:81], off
	global_load_dwordx4 v[140:143], v[80:81], off offset:64
	global_load_dwordx4 v[144:147], v[80:81], off offset:128
	global_load_dwordx4 v[148:151], v[80:81], off offset:192
	v_min_i32_e32 v80, s0, v82
	v_ashrrev_i32_e32 v81, 31, v80
	v_lshlrev_b64 v[80:81], 7, v[80:81]
	v_cmp_lt_i32_e32 vcc, -1, v82
	s_cmpk_gt_i32 s14, 0x11ff
	s_nop 0
	v_cndmask_b32_e32 v81, 0, v81, vcc
	v_cndmask_b32_e32 v80, 0, v80, vcc
	v_lshl_add_u64 v[80:81], v[80:81], 1, v[2:3]
	global_load_dwordx4 v[152:155], v[80:81], off
	global_load_dwordx4 v[156:159], v[80:81], off offset:64
	global_load_dwordx4 v[160:163], v[80:81], off offset:128
	global_load_dwordx4 v[164:167], v[80:81], off offset:192
	v_min_i32_e32 v80, s0, v0
	v_ashrrev_i32_e32 v81, 31, v80
	v_lshlrev_b64 v[80:81], 7, v[80:81]
	v_cmp_lt_i32_e32 vcc, -1, v0
	s_nop 1
	v_cndmask_b32_e32 v81, 0, v81, vcc
	v_cndmask_b32_e32 v80, 0, v80, vcc
	v_lshl_add_u64 v[2:3], v[80:81], 1, v[2:3]
	global_load_dwordx4 v[176:179], v[2:3], off
	global_load_dwordx4 v[172:175], v[2:3], off offset:64
	global_load_dwordx4 v[168:171], v[2:3], off offset:128
	global_load_dwordx4 v[116:119], v[2:3], off offset:192
	s_cbranch_scc1 .LBB0_451
	s_lshl_b32 s0, s14, 1
	s_add_i32 s0, s0, s94
	s_mul_hi_i32 s1, s0, 0x2aaaaaab
	s_lshr_b32 s14, s1, 31
	s_ashr_i32 s1, s1, 7
	s_add_i32 s14, s1, s14
	s_mul_i32 s1, s14, 0xfffffd00
	s_add_i32 s1, s1, s0
	s_lshl_b32 s0, s1, 6
	s_and_b32 s16, s0, 0xffffe000
	s_cmpk_lt_i32 s1, 0x200
	s_cselect_b32 s1, 13, 14
	s_cselect_b32 s16, s16, 0x8000
	s_ashr_i32 s17, s14, 1
	s_and_b32 s17, s17, -2
	s_sub_i32 s1, s1, s17
	s_lshl_b32 s18, 1, s1
	s_sub_i32 s0, s0, s16
	s_lshl_b32 s1, -1, s1
	s_and_b32 s17, s1, s0
	s_sub_i32 s19, s0, s17
	s_cmp_lt_i32 s19, 64
	s_cbranch_scc1 .Lattn_vslow
	s_add_i32 s0, s19, 0x80
	s_cmp_gt_i32 s0, s18
	s_cbranch_scc1 .Lattn_vslow
	s_add_i32 s28, s14, 24
	s_mul_i32 s28, s28, 0xc000
	s_add_i32 s28, s28, s16
	s_add_i32 s28, s28, s17
	s_add_i32 s28, s28, s19
	v_add_u32_e32 v0, s28, v220
	v_lshlrev_b32_e32 v0, 8, v0
	s_mov_b64 s[28:29], 0x1000
	v_lshl_add_u64 v[2:3], v[188:189], 0, v[0:1]
	v_lshl_add_u64 v[2:3], s[28:29], 0, v[2:3]
	s_mov_b64 s[28:29], 0x2000
	global_load_dwordx4 v[8:11], v[2:3], off offset:-4096
	global_load_dwordx4 v[4:7], v[2:3], off
	v_lshl_add_u64 v[2:3], s[28:29], 0, v[2:3]
	global_load_dwordx4 v[12:15], v[2:3], off offset:-4096
	global_load_dwordx4 v[16:19], v[2:3], off
	v_lshl_add_u64 v[2:3], s[28:29], 0, v[2:3]
	global_load_dwordx4 v[20:23], v[2:3], off offset:-4096
	global_load_dwordx4 v[24:27], v[2:3], off
	v_lshl_add_u64 v[2:3], s[28:29], 0, v[2:3]
	global_load_dwordx4 v[28:31], v[2:3], off offset:-4096
	global_load_dwordx4 v[32:35], v[2:3], off
	v_lshl_add_u64 v[2:3], s[28:29], 0, v[2:3]
	global_load_dwordx4 v[36:39], v[2:3], off offset:-4096
	global_load_dwordx4 v[40:43], v[2:3], off
	v_lshl_add_u64 v[2:3], s[28:29], 0, v[2:3]
	global_load_dwordx4 v[44:47], v[2:3], off offset:-4096
	global_load_dwordx4 v[48:51], v[2:3], off
	s_branch .LBB0_451
